# attention deal: 64 instead of 96 workgroups start on the sample stream
# baseline (speedup 1.0000x reference)
.LBB0_1954:
	s_and_b64 vcc, exec, s[6:7]
	s_cbranch_vccz .LBB0_2686
	v_writelane_b32 v255, s86, 12
	s_cmpk_lt_i32 s2, 0xc0
	s_mov_b64 s[4:5], -1
	v_writelane_b32 v255, s87, 13
	v_writelane_b32 v255, s97, 14
	v_writelane_b32 v255, s85, 15
	v_writelane_b32 v255, s88, 16
	s_cbranch_scc0 .LBB0_2321
	s_mov_b64 s[0:1], s[86:87]
	s_load_dwordx2 s[6:7], s[0:1], 0x118
	s_load_dwordx2 s[8:9], s[0:1], 0xb8
	s_bfe_u32 s4, s2, 0x20001
	s_lshl_b32 s5, s4, 8
	v_mbcnt_lo_u32_b32 v2, -1, 0
	s_waitcnt lgkmcnt(0)
	s_add_u32 s0, s6, s5
	s_addc_u32 s1, s7, 0
	s_add_u32 s58, s0, 0xc44a0
	s_addc_u32 s59, s1, 0
	s_lshl_b32 s10, s4, 2
	s_add_u32 s60, s0, 0x29600000
	s_addc_u32 s61, s1, 0
	s_lshl_b32 s0, s4, 21
	s_add_u32 s0, s6, s0
	s_addc_u32 s1, s7, 0
	s_add_u32 s0, s0, 0x2a600000
	s_addc_u32 s1, s1, 0
	s_lshr_b32 s11, s88, 7
	s_bfe_u32 s12, s88, 0x10006
	s_add_i32 s11, s11, s10
	s_lshl_b32 s33, s12, 5
	s_lshl_b32 s10, s11, 8
	s_add_u32 s6, s6, s10
	s_addc_u32 s7, s7, 0
	s_add_u32 s62, s6, 0x2ae00000
	s_addc_u32 s63, s7, 0
	s_lshl_b32 s10, s11, 2
	s_add_u32 s64, s8, s10
	s_addc_u32 s65, s9, 0
	s_lshl_b32 s8, s85, 1
	s_or_b32 s8, s8, 1
	s_lshl_b32 s48, s85, 3
	s_lshl_b32 s49, s85, 11
	s_lshl_b32 s51, s85, 4
	s_lshl_b32 s52, s8, 2
	s_lshl_b32 s53, s8, 10
	s_lshl_b32 s56, s8, 3
	s_and_b32 s8, 64, s88
	s_cmp_eq_u32 s12, 0
	s_cselect_b64 s[66:67], -1, 0
	s_cmp_lg_u32 s8, 0
	s_cselect_b64 s[68:69], -1, 0
	s_add_u32 s70, s6, 0x2d200000
	s_addc_u32 s71, s7, 0
	s_add_i32 s57, 0, 0x20180
	s_mov_b32 s47, 0
	v_cmp_eq_u32_e64 s[4:5], 0, v0
	v_mov_b32_e32 v157, 0
	s_movk_i32 s74, 0x7f
	s_mov_b32 s75, 0x5040100
	s_movk_i32 s76, 0x60
	v_mov_b32_e32 v168, s57
	v_mov_b32_e32 v169, 0x3f80
	v_mov_b32_e32 v170, 0xff800000
	v_mbcnt_hi_u32_b32 v223, -1, v2
	v_mov_b32_e32 v171, 0xffffbf80
	v_mov_b32_e32 v172, 0x60
	s_branch .LBB0_1960
